# adds gate-sigmoid epilogue bias-load hoist and one static priority raise for waves 4-7 during the attention phase (per-segment setprio toggles removed)
# baseline (speedup 1.0000x reference)
.LBB0_570:
	v_readfirstlane_b32 s4, v0
	s_cmp_ge_u32 s4, 0x100
	s_cbranch_scc0 .Lprio_skip
	s_setprio 1

.LBB0_635:
	v_lshl_add_u64 v[66:67], s[10:11], 0, v[184:185]
	v_lshl_add_u64 v[68:69], s[10:11], 0, v[186:187]
	global_load_dwordx4 v[162:165], v[66:67], off
	global_load_dwordx4 v[154:157], v[68:69], off
	v_lshl_add_u64 v[66:67], s[10:11], 0, v[178:179]
	v_lshl_add_u64 v[68:69], s[10:11], 0, v[180:181]
	global_load_dwordx4 v[158:161], v[66:67], off
	global_load_dwordx4 v[146:149], v[68:69], off
	v_lshl_add_u64 v[66:67], s[10:11], 0, v[182:183]
	global_load_dwordx4 v[150:153], v[66:67], off
	s_and_b32 s19, s17, 1
	s_nop 0
	s_mul_i32 s6, s19, 0x6000
	v_add_u32_e32 v212, s6, v213
	v_add_u32_e32 v236, v212, v230
	v_add_u32_e32 v70, v212, v229
	ds_read_b128 v[232:235], v236 offset:32768
	ds_read_b128 v[242:245], v236 offset:45056
	ds_read_b128 v[246:249], v70 offset:32768
	ds_read_b128 v[250:253], v70 offset:45056
	s_waitcnt vmcnt(16) lgkmcnt(3)
	v_mfma_f32_32x32x16_bf16 v[82:97], v[232:235], v[142:145], 0
	v_add_u32_e32 v236, v212, v228
	ds_read_b128 v[232:235], v236 offset:32768
	s_waitcnt lgkmcnt(3)
	v_mfma_f32_32x32x16_bf16 v[66:81], v[242:245], v[142:145], 0
	ds_read_b128 v[242:245], v236 offset:45056
	s_waitcnt vmcnt(15) lgkmcnt(3)
	v_mfma_f32_32x32x16_bf16 v[82:97], v[246:249], v[138:141], v[82:97]
	v_add_u32_e32 v236, v212, v226
	ds_read_b128 v[246:249], v236 offset:32768
	s_waitcnt lgkmcnt(3)
	v_mfma_f32_32x32x16_bf16 v[66:81], v[250:253], v[138:141], v[66:81]
	ds_read_b128 v[250:253], v236 offset:45056
	s_waitcnt vmcnt(14) lgkmcnt(3)
	v_mfma_f32_32x32x16_bf16 v[82:97], v[232:235], v[134:137], v[82:97]
	v_add_u32_e32 v236, v212, v222
	ds_read_b128 v[232:235], v236 offset:32768
	s_waitcnt lgkmcnt(3)
	v_mfma_f32_32x32x16_bf16 v[66:81], v[242:245], v[134:137], v[66:81]
	ds_read_b128 v[242:245], v236 offset:45056
	s_waitcnt vmcnt(13) lgkmcnt(3)
	v_mfma_f32_32x32x16_bf16 v[82:97], v[246:249], v[130:133], v[82:97]
	v_add_u32_e32 v236, v212, v220
	ds_read_b128 v[246:249], v236 offset:32768
	s_waitcnt lgkmcnt(3)
	v_mfma_f32_32x32x16_bf16 v[66:81], v[250:253], v[130:133], v[66:81]
	ds_read_b128 v[250:253], v236 offset:45056
	s_waitcnt vmcnt(12) lgkmcnt(3)
	v_mfma_f32_32x32x16_bf16 v[82:97], v[232:235], v[126:129], v[82:97]
	v_add_u32_e32 v236, v212, v219
	ds_read_b128 v[232:235], v236 offset:32768
	s_waitcnt lgkmcnt(3)
	v_mfma_f32_32x32x16_bf16 v[66:81], v[242:245], v[126:129], v[66:81]
	ds_read_b128 v[242:245], v236 offset:45056
	s_waitcnt vmcnt(11) lgkmcnt(3)
	v_mfma_f32_32x32x16_bf16 v[82:97], v[246:249], v[122:125], v[82:97]
	v_add_u32_e32 v236, v212, v218
	ds_read_b128 v[246:249], v236 offset:32768
	s_waitcnt lgkmcnt(3)
	v_mfma_f32_32x32x16_bf16 v[66:81], v[250:253], v[122:125], v[66:81]
	ds_read_b128 v[250:253], v236 offset:45056
	s_waitcnt vmcnt(10) lgkmcnt(3)
	v_mfma_f32_32x32x16_bf16 v[82:97], v[232:235], v[118:121], v[82:97]
	v_add_u32_e32 v236, v212, v217
	ds_read_b128 v[232:235], v236 offset:32768
	s_waitcnt lgkmcnt(3)
	v_mfma_f32_32x32x16_bf16 v[66:81], v[242:245], v[118:121], v[66:81]
	ds_read_b128 v[242:245], v236 offset:45056
	s_waitcnt vmcnt(9) lgkmcnt(3)
	v_mfma_f32_32x32x16_bf16 v[82:97], v[246:249], v[114:117], v[82:97]
	v_add_u32_e32 v236, v212, v216
	ds_read_b128 v[246:249], v236 offset:32768
	s_waitcnt lgkmcnt(3)
	v_mfma_f32_32x32x16_bf16 v[66:81], v[250:253], v[114:117], v[66:81]
	ds_read_b128 v[250:253], v236 offset:45056
	s_waitcnt vmcnt(8) lgkmcnt(3)
	v_mfma_f32_32x32x16_bf16 v[82:97], v[232:235], v[110:113], v[82:97]
	v_add_u32_e32 v236, v212, v215
	ds_read_b128 v[232:235], v236 offset:32768
	s_waitcnt lgkmcnt(3)
	v_mfma_f32_32x32x16_bf16 v[66:81], v[242:245], v[110:113], v[66:81]
	ds_read_b128 v[242:245], v236 offset:45056
	s_waitcnt vmcnt(7) lgkmcnt(3)
	v_mfma_f32_32x32x16_bf16 v[82:97], v[246:249], v[106:109], v[82:97]
	v_add_u32_e32 v212, v212, v214
	ds_read_b128 v[246:249], v212 offset:32768
	s_waitcnt lgkmcnt(3)
	v_mfma_f32_32x32x16_bf16 v[66:81], v[250:253], v[106:109], v[66:81]
	ds_read_b128 v[250:253], v212 offset:45056
	s_waitcnt vmcnt(6) lgkmcnt(3)
	v_mfma_f32_32x32x16_bf16 v[82:97], v[232:235], v[102:105], v[82:97]
	s_waitcnt lgkmcnt(2)
	v_mfma_f32_32x32x16_bf16 v[66:81], v[242:245], v[102:105], v[66:81]
	s_waitcnt vmcnt(5) lgkmcnt(1)
	v_mfma_f32_32x32x16_bf16 v[82:97], v[246:249], v[98:101], v[82:97]
	s_waitcnt lgkmcnt(0)
	v_mfma_f32_32x32x16_bf16 v[66:81], v[250:253], v[98:101], v[66:81]
	s_nop 0
	s_nop 7
	v_max_f32_e32 v212, v83, v83
	v_max_f32_e32 v232, v82, v82
	v_max_f32_e32 v212, v232, v212
	v_max3_f32 v212, v212, v84, v85
	v_max3_f32 v212, v212, v86, v87
	v_max3_f32 v212, v212, v88, v89
	v_max3_f32 v212, v212, v90, v91
	v_max3_f32 v212, v212, v92, v93
	v_max3_f32 v212, v212, v94, v95
	v_max3_f32 v212, v212, v96, v97
	v_max3_f32 v212, v212, v66, v67
	v_max3_f32 v212, v212, v68, v69
	v_max3_f32 v212, v212, v70, v71
	v_max3_f32 v212, v212, v72, v73
	v_max3_f32 v212, v212, v74, v75
	v_max3_f32 v212, v212, v76, v77
	v_max3_f32 v212, v212, v78, v79
	v_max3_f32 v212, v212, v80, v81
	v_mov_b32_e32 v232, v212
	s_nop 1
	v_permlane32_swap_b32_e32 v212, v232
	v_max_f32_e32 v232, v232, v232
	v_max_f32_e32 v212, v212, v212
	v_max_f32_e32 v212, v212, v232
	v_sub_f32_e32 v232, v212, v211
	v_cmp_ge_f32_e32 vcc, s41, v232
	v_max_f32_e32 v232, v211, v211
	v_max_f32_e32 v212, v232, v212
	v_sub_f32_e32 v232, v211, v212
	v_mul_f32_e32 v232, 0x3dd53b94, v232
	v_exp_f32_e32 v232, v232
	s_cmp_eq_u64 vcc, exec
	s_cselect_b64 s[6:7], -1, 0
	v_cndmask_b32_e64 v232, v232, 1.0, s[6:7]
	v_cmp_gt_f32_e32 vcc, 1.0, v232
	s_cbranch_vccz .LBB0_639
	s_and_saveexec_b64 s[12:13], s[4:5]
	ds_write_b32 v209, v232 offset:128
	s_or_b64 exec, exec, s[12:13]
	s_waitcnt lgkmcnt(0)
	v_add_u32_e32 v233, v208, v166
	ds_read_b128 v[234:237], v233 offset:224
	ds_read_b128 v[242:245], v233 offset:192
	ds_read_b128 v[246:249], v233 offset:160
	ds_read_b128 v[250:253], v233 offset:128
	s_waitcnt lgkmcnt(3)
	v_pk_mul_f32 v[14:15], v[14:15], v[234:235]
	s_waitcnt lgkmcnt(2)
	v_pk_mul_f32 v[10:11], v[10:11], v[242:243]
	s_waitcnt lgkmcnt(1)
	v_pk_mul_f32 v[6:7], v[6:7], v[246:247]
	v_pk_mul_f32 v[16:17], v[16:17], v[236:237]
	v_pk_mul_f32 v[12:13], v[12:13], v[244:245]
	v_pk_mul_f32 v[8:9], v[8:9], v[248:249]
	s_waitcnt lgkmcnt(0)
	v_pk_mul_f32 v[4:5], v[4:5], v[252:253]
	v_pk_mul_f32 v[2:3], v[2:3], v[250:251]
	v_pk_mul_f32 v[62:63], v[62:63], v[234:235]
	v_pk_mul_f32 v[58:59], v[58:59], v[242:243]
	v_pk_mul_f32 v[54:55], v[54:55], v[246:247]
	v_pk_mul_f32 v[64:65], v[64:65], v[236:237]
	v_pk_mul_f32 v[60:61], v[60:61], v[244:245]
	v_pk_mul_f32 v[56:57], v[56:57], v[248:249]
	v_pk_mul_f32 v[52:53], v[52:53], v[252:253]
	v_pk_mul_f32 v[50:51], v[50:51], v[250:251]
	v_pk_mul_f32 v[46:47], v[46:47], v[234:235]
	v_pk_mul_f32 v[42:43], v[42:43], v[242:243]
	v_pk_mul_f32 v[38:39], v[38:39], v[246:247]
	v_pk_mul_f32 v[48:49], v[48:49], v[236:237]
	v_pk_mul_f32 v[44:45], v[44:45], v[244:245]
	v_pk_mul_f32 v[40:41], v[40:41], v[248:249]
	v_pk_mul_f32 v[36:37], v[36:37], v[252:253]
	v_pk_mul_f32 v[34:35], v[34:35], v[250:251]
	v_pk_mul_f32 v[30:31], v[30:31], v[234:235]
	v_pk_mul_f32 v[26:27], v[26:27], v[242:243]
	v_pk_mul_f32 v[22:23], v[22:23], v[246:247]
	v_pk_mul_f32 v[32:33], v[32:33], v[236:237]
	v_pk_mul_f32 v[28:29], v[28:29], v[244:245]
	v_pk_mul_f32 v[24:25], v[24:25], v[248:249]
	v_pk_mul_f32 v[20:21], v[20:21], v[252:253]
	v_pk_mul_f32 v[18:19], v[18:19], v[250:251]
.LBB0_639:
	v_cndmask_b32_e64 v211, v212, v211, s[6:7]
	v_mul_f32_e32 v212, 0xbdd53b94, v211
	v_fmamk_f32 v82, v82, 0x3dd53b94, v212
	v_fmamk_f32 v83, v83, 0x3dd53b94, v212
	v_fmamk_f32 v84, v84, 0x3dd53b94, v212
	v_fmamk_f32 v85, v85, 0x3dd53b94, v212
	v_fmamk_f32 v86, v86, 0x3dd53b94, v212
	v_fmamk_f32 v87, v87, 0x3dd53b94, v212
	v_fmamk_f32 v88, v88, 0x3dd53b94, v212
	v_fmamk_f32 v89, v89, 0x3dd53b94, v212
	v_fmamk_f32 v90, v90, 0x3dd53b94, v212
	v_fmamk_f32 v91, v91, 0x3dd53b94, v212
	v_fmamk_f32 v92, v92, 0x3dd53b94, v212
	v_fmamk_f32 v93, v93, 0x3dd53b94, v212
	v_fmamk_f32 v94, v94, 0x3dd53b94, v212
	v_fmamk_f32 v95, v95, 0x3dd53b94, v212
	v_fmamk_f32 v96, v96, 0x3dd53b94, v212
	v_fmamk_f32 v97, v97, 0x3dd53b94, v212
	v_fmamk_f32 v66, v66, 0x3dd53b94, v212
	v_fmamk_f32 v67, v67, 0x3dd53b94, v212
	v_fmamk_f32 v68, v68, 0x3dd53b94, v212
	v_fmamk_f32 v69, v69, 0x3dd53b94, v212
	v_fmamk_f32 v70, v70, 0x3dd53b94, v212
	v_fmamk_f32 v71, v71, 0x3dd53b94, v212
	v_fmamk_f32 v72, v72, 0x3dd53b94, v212
	v_fmamk_f32 v73, v73, 0x3dd53b94, v212
	v_fmamk_f32 v74, v74, 0x3dd53b94, v212
	v_fmamk_f32 v75, v75, 0x3dd53b94, v212
	v_fmamk_f32 v76, v76, 0x3dd53b94, v212
	v_fmamk_f32 v77, v77, 0x3dd53b94, v212
	v_fmamk_f32 v78, v78, 0x3dd53b94, v212
	v_fmamk_f32 v79, v79, 0x3dd53b94, v212
	v_fmamk_f32 v80, v80, 0x3dd53b94, v212
	v_fmac_f32_e32 v212, 0x3dd53b94, v81
	v_exp_f32_e32 v81, v82
	v_exp_f32_e32 v82, v83
	v_exp_f32_e32 v83, v84
	v_exp_f32_e32 v84, v85
	v_exp_f32_e32 v85, v86
	v_exp_f32_e32 v86, v87
	v_exp_f32_e32 v87, v88
	v_exp_f32_e32 v88, v89
	v_exp_f32_e32 v89, v90
	v_exp_f32_e32 v90, v91
	v_exp_f32_e32 v91, v92
	v_exp_f32_e32 v92, v93
	v_exp_f32_e32 v93, v94
	v_exp_f32_e32 v94, v95
	v_exp_f32_e32 v95, v96
	v_exp_f32_e32 v96, v97
	v_exp_f32_e32 v97, v66
	v_add_f32_e32 v66, 0, v81
	v_add_f32_e32 v66, v82, v66
	v_add_f32_e32 v66, v83, v66
	v_add_f32_e32 v66, v84, v66
	v_add_f32_e32 v66, v85, v66
	v_add_f32_e32 v66, v86, v66
	v_add_f32_e32 v66, v87, v66
	v_add_f32_e32 v66, v88, v66
	v_add_f32_e32 v66, v89, v66
	v_add_f32_e32 v66, v90, v66
	v_add_f32_e32 v66, v91, v66
	v_add_f32_e32 v66, v92, v66
	v_add_f32_e32 v66, v93, v66
	v_exp_f32_e32 v233, v67
	v_add_f32_e32 v66, v94, v66
	v_exp_f32_e32 v234, v68
	v_add_f32_e32 v66, v95, v66
	v_exp_f32_e32 v235, v69
	v_add_f32_e32 v66, v96, v66
	v_exp_f32_e32 v236, v70
	v_add_f32_e32 v66, v97, v66
	v_exp_f32_e32 v237, v71
	v_add_f32_e32 v66, v233, v66
	v_exp_f32_e32 v242, v72
	v_add_f32_e32 v66, v234, v66
	v_exp_f32_e32 v243, v73
	v_add_f32_e32 v66, v235, v66
	v_exp_f32_e32 v244, v74
	v_add_f32_e32 v66, v236, v66
	v_exp_f32_e32 v245, v75
	v_add_f32_e32 v66, v237, v66
	v_exp_f32_e32 v246, v76
	v_add_f32_e32 v66, v242, v66
	v_exp_f32_e32 v247, v77
	v_add_f32_e32 v66, v243, v66
	v_exp_f32_e32 v248, v78
	v_add_f32_e32 v66, v244, v66
	v_exp_f32_e32 v249, v79
	v_add_f32_e32 v66, v245, v66
	v_exp_f32_e32 v250, v80
	v_add_f32_e32 v66, v246, v66
	v_exp_f32_e32 v251, v212
	v_add_f32_e32 v66, v247, v66
	v_add_f32_e32 v66, v248, v66
	v_add_f32_e32 v66, v249, v66
	v_add_f32_e32 v66, v250, v66
	v_add_f32_e32 v66, v251, v66
	v_mov_b32_e32 v67, v66
	s_nop 1
	v_permlane32_swap_b32_e32 v66, v67
	v_add_f32_e32 v212, v66, v67
	s_add_i32 s17, s17, 1
	v_fmac_f32_e32 v212, v231, v232
	v_cvt_pk_bf16_f32 v66, v81, v82
	v_cvt_pk_bf16_f32 v67, v83, v84
	v_cvt_pk_bf16_f32 v68, v85, v86
	v_cvt_pk_bf16_f32 v69, v87, v88
	v_cvt_pk_bf16_f32 v70, v89, v90
	v_cvt_pk_bf16_f32 v71, v91, v92
	v_cvt_pk_bf16_f32 v72, v93, v94
	v_cvt_pk_bf16_f32 v73, v95, v96
	v_cvt_pk_bf16_f32 v74, v97, v233
	v_cvt_pk_bf16_f32 v75, v234, v235
	v_cvt_pk_bf16_f32 v76, v236, v237
	v_cvt_pk_bf16_f32 v77, v242, v243
	v_cvt_pk_bf16_f32 v78, v244, v245
	v_cvt_pk_bf16_f32 v79, v246, v247
	v_cvt_pk_bf16_f32 v80, v248, v249
	v_cvt_pk_bf16_f32 v81, v250, v251
	v_permlane32_swap_b32_e32 v66, v68
	v_permlane32_swap_b32_e32 v67, v69
	v_permlane32_swap_b32_e32 v70, v72
	v_permlane32_swap_b32_e32 v71, v73
	v_permlane32_swap_b32_e32 v74, v76
	v_permlane32_swap_b32_e32 v75, v77
	v_permlane32_swap_b32_e32 v78, v80
	v_permlane32_swap_b32_e32 v79, v81
	v_lshl_add_u32 v231, s19, 14, v210
	s_nop 0
	ds_read_b64_tr_b16 v[82:83], v231 offset:0
	ds_read_b64_tr_b16 v[84:85], v231 offset:0x800
	ds_read_b64_tr_b16 v[86:87], v231 offset:0x1000
	ds_read_b64_tr_b16 v[88:89], v231 offset:0x1800
	ds_read_b64_tr_b16 v[90:91], v231 offset:0x2000
	ds_read_b64_tr_b16 v[92:93], v231 offset:0x2800
	ds_read_b64_tr_b16 v[94:95], v231 offset:0x3000
	ds_read_b64_tr_b16 v[96:97], v231 offset:0x3800
	s_nop 0
	s_waitcnt lgkmcnt(6)
	v_mfma_f32_32x32x16_bf16 v[2:17], v[66:69], v[82:85], v[2:17]
	ds_read_b64_tr_b16 v[82:83], v231 offset:0x200
	ds_read_b64_tr_b16 v[84:85], v231 offset:0xa00
	s_waitcnt lgkmcnt(6)
	v_mfma_f32_32x32x16_bf16 v[2:17], v[70:73], v[86:89], v[2:17]
	ds_read_b64_tr_b16 v[86:87], v231 offset:0x1200
	ds_read_b64_tr_b16 v[88:89], v231 offset:0x1a00
	s_waitcnt lgkmcnt(6)
	v_mfma_f32_32x32x16_bf16 v[2:17], v[74:77], v[90:93], v[2:17]
	ds_read_b64_tr_b16 v[90:91], v231 offset:0x2200
	ds_read_b64_tr_b16 v[92:93], v231 offset:0x2a00
	s_waitcnt lgkmcnt(6)
	v_mfma_f32_32x32x16_bf16 v[2:17], v[78:81], v[94:97], v[2:17]
	ds_read_b64_tr_b16 v[94:95], v231 offset:0x3200
	ds_read_b64_tr_b16 v[96:97], v231 offset:0x3a00
	s_waitcnt lgkmcnt(6)
	v_mfma_f32_32x32x16_bf16 v[50:65], v[66:69], v[82:85], v[50:65]
	ds_read_b64_tr_b16 v[82:83], v231 offset:0x400
	ds_read_b64_tr_b16 v[84:85], v231 offset:0xc00
	s_waitcnt lgkmcnt(6)
	v_mfma_f32_32x32x16_bf16 v[50:65], v[70:73], v[86:89], v[50:65]
	ds_read_b64_tr_b16 v[86:87], v231 offset:0x1400
	ds_read_b64_tr_b16 v[88:89], v231 offset:0x1c00
	s_waitcnt lgkmcnt(6)
	v_mfma_f32_32x32x16_bf16 v[50:65], v[74:77], v[90:93], v[50:65]
	ds_read_b64_tr_b16 v[90:91], v231 offset:0x2400
	ds_read_b64_tr_b16 v[92:93], v231 offset:0x2c00
	s_waitcnt lgkmcnt(6)
	v_mfma_f32_32x32x16_bf16 v[50:65], v[78:81], v[94:97], v[50:65]
	ds_read_b64_tr_b16 v[94:95], v231 offset:0x3400
	ds_read_b64_tr_b16 v[96:97], v231 offset:0x3c00
	s_waitcnt lgkmcnt(6)
	v_mfma_f32_32x32x16_bf16 v[34:49], v[66:69], v[82:85], v[34:49]
	ds_read_b64_tr_b16 v[82:83], v231 offset:0x600
	ds_read_b64_tr_b16 v[84:85], v231 offset:0xe00
	s_waitcnt lgkmcnt(6)
	v_mfma_f32_32x32x16_bf16 v[34:49], v[70:73], v[86:89], v[34:49]
	ds_read_b64_tr_b16 v[86:87], v231 offset:0x1600
	ds_read_b64_tr_b16 v[88:89], v231 offset:0x1e00
	s_waitcnt lgkmcnt(6)
	v_mfma_f32_32x32x16_bf16 v[34:49], v[74:77], v[90:93], v[34:49]
	ds_read_b64_tr_b16 v[90:91], v231 offset:0x2600
	ds_read_b64_tr_b16 v[92:93], v231 offset:0x2e00
	s_waitcnt lgkmcnt(6)
	v_mfma_f32_32x32x16_bf16 v[34:49], v[78:81], v[94:97], v[34:49]
	ds_read_b64_tr_b16 v[94:95], v231 offset:0x3600
	ds_read_b64_tr_b16 v[96:97], v231 offset:0x3e00
	s_waitcnt lgkmcnt(6)
	v_mfma_f32_32x32x16_bf16 v[18:33], v[66:69], v[82:85], v[18:33]
	s_waitcnt lgkmcnt(4)
	v_mfma_f32_32x32x16_bf16 v[18:33], v[70:73], v[86:89], v[18:33]
	s_waitcnt lgkmcnt(2)
	v_mfma_f32_32x32x16_bf16 v[18:33], v[74:77], v[90:93], v[18:33]
	s_waitcnt lgkmcnt(0)
	v_mfma_f32_32x32x16_bf16 v[18:33], v[78:81], v[94:97], v[18:33]
	s_nop 0
	s_xor_b32 s6, s19, 1
	s_lshl_b32 s7, s6, 14
	s_add_i32 s7, s7, 0
	v_add_u32_e32 v66, s7, v225
	s_lshl_b32 s6, s6, 13
	s_waitcnt vmcnt(4)
	ds_write_b128 v66, v[162:165]
	v_add_u32_e32 v66, s7, v227
	s_add_i32 s7, s7, s6
	s_waitcnt vmcnt(3)
	ds_write_b128 v66, v[154:157]
	v_add_u32_e32 v66, s7, v221
	s_waitcnt vmcnt(2)
	ds_write_b128 v66, v[158:161] offset:32768
	v_add_u32_e32 v66, s7, v223
	s_waitcnt vmcnt(1)
	ds_write_b128 v66, v[146:149] offset:32768
	v_add_u32_e32 v66, s7, v224
	v_lshl_add_u64 v[178:179], v[178:179], 0, s[56:57]
	v_lshl_add_u64 v[180:181], v[180:181], 0, s[56:57]
	v_lshl_add_u64 v[182:183], v[182:183], 0, s[56:57]
	v_lshl_add_u64 v[184:185], v[184:185], 0, s[58:59]
	s_cmp_eq_u32 s17, 31
	v_lshl_add_u64 v[186:187], v[186:187], 0, s[58:59]
	s_waitcnt vmcnt(0)
	ds_write_b128 v66, v[150:153] offset:32768
	s_waitcnt lgkmcnt(0)
	s_barrier
	s_cbranch_scc1 .LBB0_641
	v_mov_b32_e32 v231, v212
	s_branch .LBB0_635
.LBB0_641:
	v_add_u32_e32 v150, 0x8000, v213
	s_nop 0
	v_add_u32_e32 v66, v213, v230
	v_add_u32_e32 v70, v150, v230
	ds_read_b128 v[66:69], v66 offset:57344
	ds_read_b128 v[70:73], v70 offset:36864
	v_add_u32_e32 v146, v150, v229
	s_waitcnt lgkmcnt(1)
	v_mfma_f32_32x32x16_bf16 v[82:97], v[66:69], v[142:145], 0
	ds_read_b128 v[146:149], v146 offset:36864
	s_waitcnt lgkmcnt(1)
	v_mfma_f32_32x32x16_bf16 v[66:81], v[70:73], v[142:145], 0
	v_add_u32_e32 v142, v213, v229
	ds_read_b128 v[142:145], v142 offset:57344
	s_waitcnt lgkmcnt(0)
	v_mfma_f32_32x32x16_bf16 v[82:97], v[142:145], v[138:141], v[82:97]
	v_add_u32_e32 v142, v150, v228
	ds_read_b128 v[142:145], v142 offset:36864
	v_mfma_f32_32x32x16_bf16 v[66:81], v[146:149], v[138:141], v[66:81]
	v_add_u32_e32 v138, v213, v228
	ds_read_b128 v[138:141], v138 offset:57344
	s_waitcnt lgkmcnt(0)
	v_mfma_f32_32x32x16_bf16 v[82:97], v[138:141], v[134:137], v[82:97]
	v_add_u32_e32 v138, v150, v226
	ds_read_b128 v[138:141], v138 offset:36864
	v_mfma_f32_32x32x16_bf16 v[66:81], v[142:145], v[134:137], v[66:81]
	v_add_u32_e32 v134, v213, v226
	ds_read_b128 v[134:137], v134 offset:57344
	s_waitcnt lgkmcnt(0)
	v_mfma_f32_32x32x16_bf16 v[82:97], v[134:137], v[130:133], v[82:97]
	v_add_u32_e32 v134, v150, v222
	ds_read_b128 v[134:137], v134 offset:36864
	v_mfma_f32_32x32x16_bf16 v[66:81], v[138:141], v[130:133], v[66:81]
	v_add_u32_e32 v130, v213, v222
	ds_read_b128 v[130:133], v130 offset:57344
	s_waitcnt lgkmcnt(0)
	v_mfma_f32_32x32x16_bf16 v[82:97], v[130:133], v[126:129], v[82:97]
	v_add_u32_e32 v130, v150, v220
	ds_read_b128 v[130:133], v130 offset:36864
	v_mfma_f32_32x32x16_bf16 v[66:81], v[134:137], v[126:129], v[66:81]
	v_add_u32_e32 v126, v213, v220
	ds_read_b128 v[126:129], v126 offset:57344
	s_waitcnt lgkmcnt(0)
	v_mfma_f32_32x32x16_bf16 v[82:97], v[126:129], v[122:125], v[82:97]
	v_add_u32_e32 v126, v150, v219
	ds_read_b128 v[126:129], v126 offset:36864
	v_mfma_f32_32x32x16_bf16 v[66:81], v[130:133], v[122:125], v[66:81]
	v_add_u32_e32 v122, v213, v219
	ds_read_b128 v[122:125], v122 offset:57344
	s_waitcnt lgkmcnt(0)
	v_mfma_f32_32x32x16_bf16 v[82:97], v[122:125], v[118:121], v[82:97]
	v_add_u32_e32 v122, v150, v218
	ds_read_b128 v[122:125], v122 offset:36864
	v_mfma_f32_32x32x16_bf16 v[66:81], v[126:129], v[118:121], v[66:81]
	v_add_u32_e32 v118, v213, v218
	ds_read_b128 v[118:121], v118 offset:57344
	s_waitcnt lgkmcnt(0)
	v_mfma_f32_32x32x16_bf16 v[82:97], v[118:121], v[114:117], v[82:97]
	v_add_u32_e32 v118, v150, v217
	ds_read_b128 v[118:121], v118 offset:36864
	v_mfma_f32_32x32x16_bf16 v[66:81], v[122:125], v[114:117], v[66:81]
	v_add_u32_e32 v114, v213, v217
	ds_read_b128 v[114:117], v114 offset:57344
	s_waitcnt lgkmcnt(0)
	v_mfma_f32_32x32x16_bf16 v[82:97], v[114:117], v[110:113], v[82:97]
	v_add_u32_e32 v114, v150, v216
	ds_read_b128 v[114:117], v114 offset:36864
	v_mfma_f32_32x32x16_bf16 v[66:81], v[118:121], v[110:113], v[66:81]
	v_add_u32_e32 v110, v213, v216
	ds_read_b128 v[110:113], v110 offset:57344
	s_waitcnt lgkmcnt(0)
	v_mfma_f32_32x32x16_bf16 v[82:97], v[110:113], v[106:109], v[82:97]
	v_add_u32_e32 v110, v150, v215
	ds_read_b128 v[110:113], v110 offset:36864
	v_mfma_f32_32x32x16_bf16 v[66:81], v[114:117], v[106:109], v[66:81]
	v_add_u32_e32 v106, v213, v215
	ds_read_b128 v[106:109], v106 offset:57344
	s_waitcnt lgkmcnt(0)
	v_mfma_f32_32x32x16_bf16 v[82:97], v[106:109], v[102:105], v[82:97]
	v_add_u32_e32 v106, v150, v214
	ds_read_b128 v[106:109], v106 offset:36864
	v_mfma_f32_32x32x16_bf16 v[66:81], v[110:113], v[102:105], v[66:81]
	v_add_u32_e32 v102, v213, v214
	ds_read_b128 v[102:105], v102 offset:57344
	s_waitcnt lgkmcnt(0)
	v_mfma_f32_32x32x16_bf16 v[82:97], v[102:105], v[98:101], v[82:97]
	v_mfma_f32_32x32x16_bf16 v[66:81], v[106:109], v[98:101], v[66:81]
	s_nop 0
	s_nop 9
	v_max_f32_e32 v98, v83, v83
	v_max_f32_e32 v99, v82, v82
	v_max_f32_e32 v98, v99, v98
	v_max3_f32 v98, v98, v84, v85
	v_max3_f32 v98, v98, v86, v87
	v_max3_f32 v98, v98, v88, v89
	v_max3_f32 v98, v98, v90, v91
	v_max3_f32 v98, v98, v92, v93
	v_max3_f32 v98, v98, v94, v95
	v_max3_f32 v98, v98, v96, v97
	v_max3_f32 v98, v98, v66, v67
	v_max3_f32 v98, v98, v68, v69
	v_max3_f32 v98, v98, v70, v71
	v_max3_f32 v98, v98, v72, v73
	v_max3_f32 v98, v98, v74, v75
	v_max3_f32 v98, v98, v76, v77
	v_max3_f32 v98, v98, v78, v79
	v_max3_f32 v98, v98, v80, v81
	v_mov_b32_e32 v99, v98
	s_nop 1
	v_permlane32_swap_b32_e32 v98, v99
	v_max_f32_e32 v99, v99, v99
	v_max_f32_e32 v98, v98, v98
	v_max_f32_e32 v98, v98, v99
	v_sub_f32_e32 v99, v98, v211
	v_cmp_ge_f32_e32 vcc, s41, v99
	v_max_f32_e32 v99, v211, v211
	v_max_f32_e32 v99, v99, v98
	v_sub_f32_e32 v98, v211, v99
	v_mul_f32_e32 v98, 0x3dd53b94, v98
	v_exp_f32_e32 v98, v98
	s_cmp_eq_u64 vcc, exec
	s_cselect_b64 s[6:7], -1, 0
	v_cndmask_b32_e64 v98, v98, 1.0, s[6:7]
	v_cmp_gt_f32_e32 vcc, 1.0, v98
	s_cbranch_vccz .LBB0_645
	s_and_saveexec_b64 s[12:13], s[4:5]
	ds_write_b32 v209, v98 offset:128
	s_or_b64 exec, exec, s[12:13]
	s_waitcnt lgkmcnt(0)
	v_add_u32_e32 v112, v208, v166
	ds_read_b128 v[100:103], v112 offset:224
	ds_read_b128 v[104:107], v112 offset:192
	ds_read_b128 v[108:111], v112 offset:160
	ds_read_b128 v[112:115], v112 offset:128
	s_waitcnt lgkmcnt(3)
	v_pk_mul_f32 v[14:15], v[14:15], v[100:101]
	s_waitcnt lgkmcnt(2)
	v_pk_mul_f32 v[10:11], v[10:11], v[104:105]
	s_waitcnt lgkmcnt(1)
	v_pk_mul_f32 v[6:7], v[6:7], v[108:109]
	v_pk_mul_f32 v[16:17], v[16:17], v[102:103]
	v_pk_mul_f32 v[12:13], v[12:13], v[106:107]
	v_pk_mul_f32 v[8:9], v[8:9], v[110:111]
	s_waitcnt lgkmcnt(0)
	v_pk_mul_f32 v[4:5], v[4:5], v[114:115]
	v_pk_mul_f32 v[2:3], v[2:3], v[112:113]
	v_pk_mul_f32 v[62:63], v[62:63], v[100:101]
	v_pk_mul_f32 v[58:59], v[58:59], v[104:105]
	v_pk_mul_f32 v[54:55], v[54:55], v[108:109]
	v_pk_mul_f32 v[64:65], v[64:65], v[102:103]
	v_pk_mul_f32 v[60:61], v[60:61], v[106:107]
	v_pk_mul_f32 v[56:57], v[56:57], v[110:111]
	v_pk_mul_f32 v[52:53], v[52:53], v[114:115]
	v_pk_mul_f32 v[50:51], v[50:51], v[112:113]
	v_pk_mul_f32 v[46:47], v[46:47], v[100:101]
	v_pk_mul_f32 v[42:43], v[42:43], v[104:105]
	v_pk_mul_f32 v[38:39], v[38:39], v[108:109]
	v_pk_mul_f32 v[48:49], v[48:49], v[102:103]
	v_pk_mul_f32 v[44:45], v[44:45], v[106:107]
	v_pk_mul_f32 v[40:41], v[40:41], v[110:111]
	v_pk_mul_f32 v[36:37], v[36:37], v[114:115]
	v_pk_mul_f32 v[34:35], v[34:35], v[112:113]
	v_pk_mul_f32 v[30:31], v[30:31], v[100:101]
	v_pk_mul_f32 v[26:27], v[26:27], v[104:105]
	v_pk_mul_f32 v[22:23], v[22:23], v[108:109]
	v_pk_mul_f32 v[32:33], v[32:33], v[102:103]
	v_pk_mul_f32 v[28:29], v[28:29], v[106:107]
	v_pk_mul_f32 v[24:25], v[24:25], v[110:111]
	v_pk_mul_f32 v[20:21], v[20:21], v[114:115]
	v_pk_mul_f32 v[18:19], v[18:19], v[112:113]
.LBB0_645:
	v_cndmask_b32_e64 v99, v99, v211, s[6:7]
	v_mul_f32_e32 v99, 0xbdd53b94, v99
	v_fmamk_f32 v82, v82, 0x3dd53b94, v99
	v_fmamk_f32 v83, v83, 0x3dd53b94, v99
	v_fmamk_f32 v84, v84, 0x3dd53b94, v99
	v_fmamk_f32 v85, v85, 0x3dd53b94, v99
	v_fmamk_f32 v86, v86, 0x3dd53b94, v99
	v_fmamk_f32 v87, v87, 0x3dd53b94, v99
	v_fmamk_f32 v88, v88, 0x3dd53b94, v99
	v_fmamk_f32 v89, v89, 0x3dd53b94, v99
	v_fmamk_f32 v90, v90, 0x3dd53b94, v99
	v_fmamk_f32 v91, v91, 0x3dd53b94, v99
	v_fmamk_f32 v92, v92, 0x3dd53b94, v99
	v_fmamk_f32 v93, v93, 0x3dd53b94, v99
	v_fmamk_f32 v94, v94, 0x3dd53b94, v99
	v_fmamk_f32 v95, v95, 0x3dd53b94, v99
	v_fmamk_f32 v96, v96, 0x3dd53b94, v99
	v_fmamk_f32 v97, v97, 0x3dd53b94, v99
	v_fmamk_f32 v66, v66, 0x3dd53b94, v99
	v_fmamk_f32 v67, v67, 0x3dd53b94, v99
	v_fmamk_f32 v68, v68, 0x3dd53b94, v99
	v_fmamk_f32 v69, v69, 0x3dd53b94, v99
	v_fmamk_f32 v70, v70, 0x3dd53b94, v99
	v_fmamk_f32 v71, v71, 0x3dd53b94, v99
	v_fmamk_f32 v72, v72, 0x3dd53b94, v99
	v_fmamk_f32 v73, v73, 0x3dd53b94, v99
	v_fmamk_f32 v74, v74, 0x3dd53b94, v99
	v_fmamk_f32 v75, v75, 0x3dd53b94, v99
	v_fmamk_f32 v76, v76, 0x3dd53b94, v99
	v_fmamk_f32 v77, v77, 0x3dd53b94, v99
	v_fmamk_f32 v78, v78, 0x3dd53b94, v99
	v_fmamk_f32 v79, v79, 0x3dd53b94, v99
	v_fmamk_f32 v80, v80, 0x3dd53b94, v99
	v_fmac_f32_e32 v99, 0x3dd53b94, v81
	v_exp_f32_e32 v81, v82
	v_exp_f32_e32 v82, v83
	v_exp_f32_e32 v83, v84
	v_exp_f32_e32 v84, v85
	v_exp_f32_e32 v85, v86
	v_exp_f32_e32 v86, v87
	v_exp_f32_e32 v87, v88
	v_exp_f32_e32 v88, v89
	v_exp_f32_e32 v89, v90
	v_exp_f32_e32 v90, v91
	v_exp_f32_e32 v91, v92
	v_exp_f32_e32 v92, v93
	v_exp_f32_e32 v93, v94
	v_exp_f32_e32 v94, v95
	v_exp_f32_e32 v95, v96
	v_exp_f32_e32 v96, v97
	v_exp_f32_e32 v97, v66
	v_add_f32_e32 v66, 0, v81
	v_add_f32_e32 v66, v82, v66
	v_add_f32_e32 v66, v83, v66
	v_add_f32_e32 v66, v84, v66
	v_add_f32_e32 v66, v85, v66
	v_add_f32_e32 v66, v86, v66
	v_add_f32_e32 v66, v87, v66
	v_add_f32_e32 v66, v88, v66
	v_add_f32_e32 v66, v89, v66
	v_add_f32_e32 v66, v90, v66
	v_add_f32_e32 v66, v91, v66
	v_add_f32_e32 v66, v92, v66
	v_add_f32_e32 v66, v93, v66
	v_exp_f32_e32 v100, v67
	v_add_f32_e32 v66, v94, v66
	v_exp_f32_e32 v101, v68
	v_add_f32_e32 v66, v95, v66
	v_exp_f32_e32 v102, v69
	v_add_f32_e32 v66, v96, v66
	v_exp_f32_e32 v103, v70
	v_add_f32_e32 v66, v97, v66
	v_exp_f32_e32 v104, v71
	v_add_f32_e32 v66, v100, v66
	v_exp_f32_e32 v105, v72
	v_add_f32_e32 v66, v101, v66
	v_exp_f32_e32 v106, v73
	v_add_f32_e32 v66, v102, v66
	v_exp_f32_e32 v107, v74
	v_add_f32_e32 v66, v103, v66
	v_exp_f32_e32 v108, v75
	v_add_f32_e32 v66, v104, v66
	v_exp_f32_e32 v109, v76
	v_add_f32_e32 v66, v105, v66
	v_exp_f32_e32 v110, v77
	v_add_f32_e32 v66, v106, v66
	v_exp_f32_e32 v111, v78
	v_add_f32_e32 v66, v107, v66
	v_exp_f32_e32 v112, v79
	v_add_f32_e32 v66, v108, v66
	v_exp_f32_e32 v113, v80
	v_add_f32_e32 v66, v109, v66
	v_exp_f32_e32 v99, v99
	v_add_f32_e32 v66, v110, v66
	v_add_f32_e32 v66, v111, v66
	v_add_f32_e32 v66, v112, v66
	v_add_f32_e32 v66, v113, v66
	v_add_f32_e32 v66, v99, v66
	v_mov_b32_e32 v67, v66
	s_nop 1
	v_permlane32_swap_b32_e32 v66, v67
	v_cvt_pk_bf16_f32 v68, v81, v82
	v_cvt_pk_bf16_f32 v69, v83, v84
	v_cvt_pk_bf16_f32 v70, v85, v86
	v_cvt_pk_bf16_f32 v71, v87, v88
	v_cvt_pk_bf16_f32 v72, v89, v90
	v_cvt_pk_bf16_f32 v73, v91, v92
	v_cvt_pk_bf16_f32 v74, v93, v94
	v_cvt_pk_bf16_f32 v75, v95, v96
	v_cvt_pk_bf16_f32 v76, v97, v100
	v_cvt_pk_bf16_f32 v77, v101, v102
	v_cvt_pk_bf16_f32 v78, v103, v104
	v_cvt_pk_bf16_f32 v79, v105, v106
	v_cvt_pk_bf16_f32 v80, v107, v108
	v_cvt_pk_bf16_f32 v81, v109, v110
	v_cvt_pk_bf16_f32 v82, v111, v112
	v_cvt_pk_bf16_f32 v83, v113, v99
	v_permlane32_swap_b32_e32 v68, v70
	v_permlane32_swap_b32_e32 v69, v71
	v_permlane32_swap_b32_e32 v72, v74
	v_permlane32_swap_b32_e32 v73, v75
	v_permlane32_swap_b32_e32 v76, v78
	v_permlane32_swap_b32_e32 v77, v79
	v_permlane32_swap_b32_e32 v80, v82
	v_permlane32_swap_b32_e32 v81, v83
	v_add_u32_e32 v96, 0x4000, v210
	s_nop 0
	ds_read_b64_tr_b16 v[84:85], v96 offset:0
	ds_read_b64_tr_b16 v[86:87], v96 offset:0x800
	ds_read_b64_tr_b16 v[88:89], v96 offset:0x1000
	ds_read_b64_tr_b16 v[90:91], v96 offset:0x1800
	ds_read_b64_tr_b16 v[92:93], v96 offset:0x2000
	ds_read_b64_tr_b16 v[94:95], v96 offset:0x2800
	ds_read_b64_tr_b16 v[100:101], v96 offset:0x3000
	ds_read_b64_tr_b16 v[102:103], v96 offset:0x3800
	s_waitcnt lgkmcnt(0)
	s_nop 0
	v_mfma_f32_32x32x16_bf16 v[2:17], v[68:71], v[84:87], v[2:17]
	ds_read_b64_tr_b16 v[84:85], v96 offset:0x200
	ds_read_b64_tr_b16 v[86:87], v96 offset:0xa00
	v_mfma_f32_32x32x16_bf16 v[2:17], v[72:75], v[88:91], v[2:17]
	ds_read_b64_tr_b16 v[88:89], v96 offset:0x1200
	ds_read_b64_tr_b16 v[90:91], v96 offset:0x1a00
	v_mfma_f32_32x32x16_bf16 v[2:17], v[76:79], v[92:95], v[2:17]
	ds_read_b64_tr_b16 v[92:93], v96 offset:0x2200
	ds_read_b64_tr_b16 v[94:95], v96 offset:0x2a00
	v_mfma_f32_32x32x16_bf16 v[2:17], v[80:83], v[100:103], v[2:17]
	ds_read_b64_tr_b16 v[100:101], v96 offset:0x3200
	ds_read_b64_tr_b16 v[102:103], v96 offset:0x3a00
	s_waitcnt lgkmcnt(0)
	v_mfma_f32_32x32x16_bf16 v[50:65], v[68:71], v[84:87], v[50:65]
	ds_read_b64_tr_b16 v[84:85], v96 offset:0x400
	ds_read_b64_tr_b16 v[86:87], v96 offset:0xc00
	v_mfma_f32_32x32x16_bf16 v[50:65], v[72:75], v[88:91], v[50:65]
	ds_read_b64_tr_b16 v[88:89], v96 offset:0x1400
	ds_read_b64_tr_b16 v[90:91], v96 offset:0x1c00
	v_mfma_f32_32x32x16_bf16 v[50:65], v[76:79], v[92:95], v[50:65]
	ds_read_b64_tr_b16 v[92:93], v96 offset:0x2400
	ds_read_b64_tr_b16 v[94:95], v96 offset:0x2c00
	v_mfma_f32_32x32x16_bf16 v[50:65], v[80:83], v[100:103], v[50:65]
	ds_read_b64_tr_b16 v[100:101], v96 offset:0x3400
	ds_read_b64_tr_b16 v[102:103], v96 offset:0x3c00
	s_waitcnt lgkmcnt(0)
	v_mfma_f32_32x32x16_bf16 v[34:49], v[68:71], v[84:87], v[34:49]
	ds_read_b64_tr_b16 v[84:85], v96 offset:0x600
	ds_read_b64_tr_b16 v[86:87], v96 offset:0xe00
	v_mfma_f32_32x32x16_bf16 v[34:49], v[72:75], v[88:91], v[34:49]
	ds_read_b64_tr_b16 v[88:89], v96 offset:0x1600
	ds_read_b64_tr_b16 v[90:91], v96 offset:0x1e00
	v_mfma_f32_32x32x16_bf16 v[34:49], v[76:79], v[92:95], v[34:49]
	ds_read_b64_tr_b16 v[92:93], v96 offset:0x2600
	ds_read_b64_tr_b16 v[94:95], v96 offset:0x2e00
	v_mfma_f32_32x32x16_bf16 v[34:49], v[80:83], v[100:103], v[34:49]
	ds_read_b64_tr_b16 v[100:101], v96 offset:0x3600
	ds_read_b64_tr_b16 v[102:103], v96 offset:0x3e00
	s_waitcnt lgkmcnt(0)
	v_mfma_f32_32x32x16_bf16 v[18:33], v[68:71], v[84:87], v[18:33]
	v_mfma_f32_32x32x16_bf16 v[18:33], v[72:75], v[88:91], v[18:33]
	v_mfma_f32_32x32x16_bf16 v[18:33], v[76:79], v[92:95], v[18:33]
	v_mfma_f32_32x32x16_bf16 v[18:33], v[80:83], v[100:103], v[18:33]
	s_nop 0
	s_barrier
	s_and_saveexec_b64 s[6:7], s[4:5]
	v_add_f32_e32 v66, v66, v67
	v_fmac_f32_e32 v66, v212, v98
	ds_write_b32 v209, v66
	s_or_b64 exec, exec, s[6:7]
	s_waitcnt lgkmcnt(0)
	v_lshl_add_u32 v74, v205, 4, v208
	ds_read_b128 v[66:69], v74
	ds_read_b128 v[70:73], v74 offset:32
	s_lshl_b64 s[4:5], s[8:9], 22
	s_add_u32 s4, s71, s4
	s_addc_u32 s5, s72, s5
	s_lshl_b32 s6, s18, 8
	s_waitcnt lgkmcnt(1)
	v_rcp_f32_e32 v75, v66
	s_add_u32 s4, s4, s6
	s_movk_i32 s6, 0x2200
	v_rcp_f32_e32 v77, v67
	v_rcp_f32_e32 v78, v68
	v_rcp_f32_e32 v79, v69
	s_waitcnt lgkmcnt(0)
	v_rcp_f32_e32 v80, v70
	ds_read_b128 v[66:69], v74 offset:64
	v_rcp_f32_e32 v81, v71
	v_rcp_f32_e32 v82, v72
	v_rcp_f32_e32 v83, v73
	ds_read_b128 v[70:73], v74 offset:96
	v_mul_lo_u32 v74, v206, s6
	v_add_u32_e32 v74, 0, v74
	v_lshl_add_u32 v84, v207, 1, v74
	s_movk_i32 s6, 0x440
	v_mul_f32_e32 v2, v2, v75
	v_mad_u32_u24 v85, v205, s6, v84
	v_cvt_pk_bf16_f32 v2, v2, s0
	s_waitcnt lgkmcnt(0)
	s_waitcnt lgkmcnt(0)
	s_barrier
	ds_write_b16 v85, v2
	v_mul_f32_e32 v2, v50, v75
	v_cvt_pk_bf16_f32 v2, v2, s0
	ds_write_b16 v85, v2 offset:64
	v_mul_f32_e32 v2, v34, v75
	v_cvt_pk_bf16_f32 v2, v2, s0
	ds_write_b16 v85, v2 offset:128
	v_mul_f32_e32 v2, v18, v75
	v_lshl_or_b32 v76, v205, 2, 1
	v_cvt_pk_bf16_f32 v2, v2, s0
	v_mul_f32_e32 v3, v3, v77
	ds_write_b16 v85, v2 offset:192
	v_mad_u32_u24 v2, v76, s26, v84
	v_cvt_pk_bf16_f32 v3, v3, s0
	ds_write_b16 v2, v3
	v_mul_f32_e32 v3, v51, v77
	v_cvt_pk_bf16_f32 v3, v3, s0
	ds_write_b16 v2, v3 offset:64
	v_mul_f32_e32 v3, v35, v77
	v_cvt_pk_bf16_f32 v3, v3, s0
	ds_write_b16 v2, v3 offset:128
	v_mul_f32_e32 v3, v19, v77
	v_cvt_pk_bf16_f32 v3, v3, s0
	ds_write_b16 v2, v3 offset:192
	v_mul_f32_e32 v3, v4, v78
	v_cvt_pk_bf16_f32 v3, v3, s0
	ds_write_b16 v2, v3 offset:272
	v_mul_f32_e32 v3, v52, v78
	v_cvt_pk_bf16_f32 v3, v3, s0
	ds_write_b16 v2, v3 offset:336
	v_mul_f32_e32 v3, v36, v78
	v_cvt_pk_bf16_f32 v3, v3, s0
	ds_write_b16 v2, v3 offset:400
	v_mul_f32_e32 v3, v20, v78
	v_cvt_pk_bf16_f32 v3, v3, s0
	ds_write_b16 v2, v3 offset:464
	v_mul_f32_e32 v3, v5, v79
	v_cvt_pk_bf16_f32 v3, v3, s0
	ds_write_b16 v2, v3 offset:544
	v_mul_f32_e32 v3, v53, v79
	v_cvt_pk_bf16_f32 v3, v3, s0
	ds_write_b16 v2, v3 offset:608
	v_mul_f32_e32 v3, v37, v79
	v_cvt_pk_bf16_f32 v3, v3, s0
	ds_write_b16 v2, v3 offset:672
	v_mul_f32_e32 v3, v21, v79
	v_cvt_pk_bf16_f32 v3, v3, s0
	ds_write_b16 v2, v3 offset:736
	v_mul_f32_e32 v3, v6, v80
	v_cvt_pk_bf16_f32 v3, v3, s0
	ds_write_b16 v2, v3 offset:1904
	v_mul_f32_e32 v3, v54, v80
	v_cvt_pk_bf16_f32 v3, v3, s0
	ds_write_b16 v2, v3 offset:1968
	v_mul_f32_e32 v3, v38, v80
	v_cvt_pk_bf16_f32 v3, v3, s0
	ds_write_b16 v2, v3 offset:2032
	v_mul_f32_e32 v3, v22, v80
	v_cvt_pk_bf16_f32 v3, v3, s0
	ds_write_b16 v2, v3 offset:2096
	v_mul_f32_e32 v3, v7, v81
	v_cvt_pk_bf16_f32 v3, v3, s0
	ds_write_b16 v2, v3 offset:2176
	v_mul_f32_e32 v3, v55, v81
	v_cvt_pk_bf16_f32 v3, v3, s0
	ds_write_b16 v2, v3 offset:2240
	v_mul_f32_e32 v3, v39, v81
	v_cvt_pk_bf16_f32 v3, v3, s0
	ds_write_b16 v2, v3 offset:2304
	v_mul_f32_e32 v3, v23, v81
	v_cvt_pk_bf16_f32 v3, v3, s0
	ds_write_b16 v2, v3 offset:2368
	v_mul_f32_e32 v3, v8, v82
	v_cvt_pk_bf16_f32 v3, v3, s0
	ds_write_b16 v2, v3 offset:2448
	v_mul_f32_e32 v3, v56, v82
	v_cvt_pk_bf16_f32 v3, v3, s0
	ds_write_b16 v2, v3 offset:2512
	v_mul_f32_e32 v3, v40, v82
	v_cvt_pk_bf16_f32 v3, v3, s0
	ds_write_b16 v2, v3 offset:2576
	v_mul_f32_e32 v3, v24, v82
	v_cvt_pk_bf16_f32 v3, v3, s0
	ds_write_b16 v2, v3 offset:2640
	v_mul_f32_e32 v3, v9, v83
	v_cvt_pk_bf16_f32 v3, v3, s0
	ds_write_b16 v2, v3 offset:2720
	v_mul_f32_e32 v3, v57, v83
	v_cvt_pk_bf16_f32 v3, v3, s0
	v_rcp_f32_e32 v66, v66
	ds_write_b16 v2, v3 offset:2784
	v_mul_f32_e32 v3, v41, v83
	v_cvt_pk_bf16_f32 v3, v3, s0
	ds_write_b16 v2, v3 offset:2848
	v_mul_f32_e32 v3, v25, v83
	v_cvt_pk_bf16_f32 v3, v3, s0
	ds_write_b16 v2, v3 offset:2912
	v_mul_f32_e32 v3, v10, v66
	v_cvt_pk_bf16_f32 v3, v3, s0
	ds_write_b16 v2, v3 offset:4080
	v_mul_f32_e32 v3, v58, v66
	v_cvt_pk_bf16_f32 v3, v3, s0
	v_rcp_f32_e32 v67, v67
	ds_write_b16 v2, v3 offset:4144
	v_mul_f32_e32 v3, v42, v66
	v_cvt_pk_bf16_f32 v3, v3, s0
	ds_write_b16 v2, v3 offset:4208
	v_mul_f32_e32 v3, v26, v66
	v_cvt_pk_bf16_f32 v3, v3, s0
	ds_write_b16 v2, v3 offset:4272
	v_mul_f32_e32 v3, v11, v67
	v_cvt_pk_bf16_f32 v3, v3, s0
	ds_write_b16 v2, v3 offset:4352
	v_mul_f32_e32 v3, v59, v67
	v_cvt_pk_bf16_f32 v3, v3, s0
	v_rcp_f32_e32 v68, v68
	ds_write_b16 v2, v3 offset:4416
	v_mul_f32_e32 v3, v43, v67
	v_cvt_pk_bf16_f32 v3, v3, s0
	ds_write_b16 v2, v3 offset:4480
	v_mul_f32_e32 v3, v27, v67
	v_cvt_pk_bf16_f32 v3, v3, s0
	ds_write_b16 v2, v3 offset:4544
	v_mul_f32_e32 v3, v12, v68
	v_cvt_pk_bf16_f32 v3, v3, s0
	ds_write_b16 v2, v3 offset:4624
	v_mul_f32_e32 v3, v60, v68
	v_cvt_pk_bf16_f32 v3, v3, s0
	v_rcp_f32_e32 v69, v69
	ds_write_b16 v2, v3 offset:4688
	v_mul_f32_e32 v3, v44, v68
	v_cvt_pk_bf16_f32 v3, v3, s0
	ds_write_b16 v2, v3 offset:4752
	v_mul_f32_e32 v3, v28, v68
	v_cvt_pk_bf16_f32 v3, v3, s0
	ds_write_b16 v2, v3 offset:4816
	v_mul_f32_e32 v3, v13, v69
	v_cvt_pk_bf16_f32 v3, v3, s0
	ds_write_b16 v2, v3 offset:4896
	v_mul_f32_e32 v3, v61, v69
	v_cvt_pk_bf16_f32 v3, v3, s0
	v_rcp_f32_e32 v70, v70
	ds_write_b16 v2, v3 offset:4960
	v_mul_f32_e32 v3, v45, v69
	v_cvt_pk_bf16_f32 v3, v3, s0
	ds_write_b16 v2, v3 offset:5024
	v_mul_f32_e32 v3, v29, v69
	v_cvt_pk_bf16_f32 v3, v3, s0
	ds_write_b16 v2, v3 offset:5088
	v_mul_f32_e32 v3, v14, v70
	v_cvt_pk_bf16_f32 v3, v3, s0
	ds_write_b16 v2, v3 offset:6256
	v_mul_f32_e32 v3, v62, v70
	v_cvt_pk_bf16_f32 v3, v3, s0
	v_rcp_f32_e32 v71, v71
	ds_write_b16 v2, v3 offset:6320
	v_mul_f32_e32 v3, v46, v70
	v_cvt_pk_bf16_f32 v3, v3, s0
	ds_write_b16 v2, v3 offset:6384
	v_mul_f32_e32 v3, v30, v70
	v_cvt_pk_bf16_f32 v3, v3, s0
	ds_write_b16 v2, v3 offset:6448
	v_mul_f32_e32 v3, v15, v71
	v_cvt_pk_bf16_f32 v3, v3, s0
	ds_write_b16 v2, v3 offset:6528
	v_mul_f32_e32 v3, v63, v71
	v_cvt_pk_bf16_f32 v3, v3, s0
	v_rcp_f32_e32 v72, v72
	ds_write_b16 v2, v3 offset:6592
	v_mul_f32_e32 v3, v47, v71
	v_cvt_pk_bf16_f32 v3, v3, s0
	ds_write_b16 v2, v3 offset:6656
	v_mul_f32_e32 v3, v31, v71
	v_cvt_pk_bf16_f32 v3, v3, s0
	ds_write_b16 v2, v3 offset:6720
	v_mul_f32_e32 v3, v16, v72
	v_cvt_pk_bf16_f32 v3, v3, s0
	ds_write_b16 v2, v3 offset:6800
	v_mul_f32_e32 v3, v64, v72
	v_cvt_pk_bf16_f32 v3, v3, s0
	v_rcp_f32_e32 v73, v73
	ds_write_b16 v2, v3 offset:6864
	v_mul_f32_e32 v3, v48, v72
	v_cvt_pk_bf16_f32 v3, v3, s0
	ds_write_b16 v2, v3 offset:6928
	v_mul_f32_e32 v3, v32, v72
	v_cvt_pk_bf16_f32 v3, v3, s0
	ds_write_b16 v2, v3 offset:6992
	v_mul_f32_e32 v3, v17, v73
	v_cvt_pk_bf16_f32 v3, v3, s0
	ds_write_b16 v2, v3 offset:7072
	v_mul_f32_e32 v3, v65, v73
	v_cvt_pk_bf16_f32 v3, v3, s0
	ds_write_b16 v2, v3 offset:7136
	v_mul_f32_e32 v3, v49, v73
	v_cvt_pk_bf16_f32 v3, v3, s0
	ds_write_b16 v2, v3 offset:7200
	v_mul_f32_e32 v3, v33, v73
	v_cvt_pk_bf16_f32 v3, v3, s0
	v_add_u32_e32 v4, s16, v188
	ds_write_b16 v2, v3 offset:7264
	v_ashrrev_i32_e32 v5, 31, v4
	s_addc_u32 s5, s5, 0
	s_waitcnt lgkmcnt(0)
	v_lshlrev_b64 v[2:3], 11, v[4:5]
	v_lshrrev_b32_e32 v1, 4, v1
	v_lshl_add_u64 v[2:3], s[4:5], 0, v[2:3]
	v_and_b32_e32 v166, 0xf0, v189
	v_or_b32_e32 v6, v4, v1
	s_movk_i32 s4, 0x800
	v_add_u32_e32 v5, v74, v166
	v_lshl_add_u64 v[2:3], v[2:3], 0, v[166:167]
	v_cmp_gt_i32_e32 vcc, s4, v6
	s_and_saveexec_b64 s[4:5], vcc
	s_cbranch_execz .LBB0_649
	v_mad_u32_u24 v6, v1, s26, v5
	ds_read_b128 v[6:9], v6
	v_lshlrev_b32_e32 v166, 11, v1
	v_lshl_add_u64 v[10:11], v[2:3], 0, v[166:167]
	s_waitcnt lgkmcnt(0)
	global_store_dwordx4 v[10:11], v[6:9], off

.LBB0_666:
	s_setprio 0
	v_mov_b64_e32 v[168:169], 0x17f
	v_mov_b64_e32 v[170:171], 0x200
	v_mov_b64_e32 v[172:173], 0x1ff
	v_mov_b64_e32 v[174:175], 0x800
	v_mov_b32_e32 v196, 0xbab64f3b
	v_mbcnt_lo_u32_b32 v197, -1, 0
	v_mbcnt_hi_u32_b32 v197, -1, v197
	v_mov_b32_e32 v198, 0x42800000
	v_not_b32_e32 v199, 63
	v_mov_b32_e32 v238, 0
	v_mov_b32_e32 v239, 0
	v_mov_b32_e32 v240, 0
	v_mov_b32_e32 v241, 0
	s_mov_b64 s[6:7], s[0:1]
	s_mov_b32 s4, s2
	s_getreg_b32 s8, hwreg(HW_REG_XCC_ID, 0, 4)
	s_waitcnt vmcnt(0)
	s_barrier
	s_mov_b64 s[4:5], exec
	v_readlane_b32 s10, v254, 0
	v_readlane_b32 s11, v254, 1
	s_and_b64 s[10:11], s[4:5], s[10:11]
	v_readlane_b32 s29, v254, 3
	s_mov_b32 s49, 0x100000
	s_mov_b64 exec, s[10:11]
	s_cbranch_execz .LBB0_719
	v_readlane_b32 s9, v254, 4
	s_load_dwordx2 s[6:7], s[6:7], 0xb0
	s_waitcnt vmcnt(0) expcnt(0) lgkmcnt(0)
	v_mov_b32_e32 v1, s9
	ds_read_b32 v3, v1
	v_readlane_b32 s9, v254, 5
	s_and_b32 s26, s8, 15
	s_waitcnt lgkmcnt(0)
	v_cmp_ne_u32_e32 vcc, 0, v3
	v_mov_b32_e32 v1, s9
	ds_read_b32 v2, v1
	s_cbranch_vccnz .LBB0_683
	s_add_u32 s8, s6, 0x2c080200
	s_addc_u32 s9, s7, 0
	s_add_u32 s10, s6, 0x2c080400
	s_addc_u32 s11, s7, 0
	s_add_u32 s12, s6, 0x2c080500
	s_addc_u32 s13, s7, 0
	s_add_u32 s16, s6, 0x2c080600
	s_addc_u32 s17, s7, 0
	s_add_u32 s18, s6, 0x2c080700
	s_addc_u32 s19, s7, 0
	s_add_u32 s20, s6, 0x2c080800
	s_addc_u32 s21, s7, 0
	s_add_u32 s22, s6, 0x2c080900
	s_addc_u32 s23, s7, 0
	s_add_u32 s60, s6, 0x2c080a00
	s_addc_u32 s61, s7, 0
	s_add_u32 s66, s6, 0x2c080b00
	s_addc_u32 s67, s7, 0
	s_add_u32 s68, s6, 0x2c080c00
	s_addc_u32 s69, s7, 0
	s_add_u32 s70, s6, 0x2c080d00
	s_addc_u32 s71, s7, 0
	s_add_u32 s72, s6, 0x2c080e00
	s_addc_u32 s73, s7, 0
	s_add_u32 s74, s6, 0x2c080f00
	s_addc_u32 s75, s7, 0
	s_add_u32 s76, s6, 0x2c081000
	s_addc_u32 s77, s7, 0
	s_add_u32 s78, s6, 0x2c081100
	s_addc_u32 s79, s7, 0
	s_add_u32 s80, s6, 0x2c081200
	s_addc_u32 s81, s7, 0
	s_add_u32 s82, s6, 0x2c081300
	s_addc_u32 s83, s7, 0
	s_mov_b32 s29, 1
	s_branch .LBB0_671
